# qk-norm phase: the wait for a row's loads no longer forces the previous row's stores to complete (counted vmcnt)
# speedup vs baseline: 1.0009x; 1.0009x over previous
; __device__ __forceinline__ u16 f2bf(float x) { return (u16)(cvtpk(x, 0.f) & 0xffffu); }
; #define wave_sum(v) wave_sum_l((v), lane)
; __device__ __forceinline__ void qknorm_phase(const Params& p, int ja, int tid, int bid) {
;     ...
;     unsigned xr1[10], xr2[10];
; #pragma unroll
;     for (int hs = 0; hs < 10; ++hs) { xr1[hs] = qr[hs * 128 + lane]; xr2[hs] = qr[hs * 128 + 64 + lane]; }
;     const u32x2 vraw = *(const u32x2*)(qr + 1280 + lane * 4);
; #pragma unroll
;     for (int hs = 0; hs < 10; ++hs) {
;       const float x1 = __uint_as_float(xr1[hs] << 16), x2 = __uint_as_float(xr2[hs] << 16);
;       const float ss = wave_sum(x1 * x1 + x2 * x2);
;       const float rstd = rsqrtf(ss * (1.f / 128.f) + EPSN);
;       const float y1 = x1 * rstd * (hs < 8 ? qg1 : kg1), y2 = x2 * rstd * (hs < 8 ? qg2 : kg2);
;       const float o1 = y1 * cs - y2 * sn, o2 = y1 * sn + y2 * cs;
;       if (hs < 8) { qr[hs * 128 + lane] = f2bf(o1); qr[hs * 128 + 64 + lane] = f2bf(o2); }
;       else { u16* kd2 = kdst + (size_t)(hs - 8) * NKEY * 128; kd2[lane] = f2bf(o1); kd2[64 + lane] = f2bf(o2); }
;     }
;     *(u32x2*)(VB + ((size_t)(b * 2 + (lane >> 5)) * NKEY + key) * 128 + (lane & 31) * 4) = vraw;
;   }
.Lq3_cs0:
	s_cmp_lt_u32 s7, 0x8800
	s_cbranch_scc0 .Lq3_wlast0
	s_cmp_lt_u32 s6, s21
	s_cbranch_scc1 .Lq3_w30
	s_waitcnt vmcnt(6) lgkmcnt(0)
	s_branch .Lq3_wd0
.Lq3_wlast0:
	s_cmp_lt_u32 s6, s21
	s_cbranch_scc1 .Lq3_w00
.Lq3_w30:
	s_waitcnt vmcnt(3) lgkmcnt(0)
	s_branch .Lq3_wd0
